# idle-slot tile split retuned: 2600 tiles (50 per idle workgroup) in q0, 2040 left in q3; static priority as v140
# baseline (speedup 1.0000x reference)
.LBB0_139:
	s_barrier
	v_readlane_b32 s4, v239, 37
	v_readlane_b32 s5, v241, 0
	v_readlane_b32 s6, v241, 9
	s_cmp_lg_u32 s4, 0
	s_cbranch_scc1 .LBB0_140
	s_cmpk_lt_i32 s5, 0xcc
	s_cbranch_scc1 .LBB0_140
	s_cmpk_lg_i32 s6, 0x100
	s_cbranch_scc1 .LBB0_140
	s_add_i32 s56, s5, 0xffffff34
	s_mov_b32 s8, 0
	v_readlane_b32 s14, v239, 42
	v_readlane_b32 s15, v239, 43
	v_lshrrev_b32_e32 v117, 5, v178
	v_and_b32_e32 v168, 31, v178
	v_lshlrev_b32_e32 v116, 2, v168
	v_mul_u32_u24_e32 v16, 0x204, v117
	v_lshl_add_u32 v16, v116, 2, v16
	v_and_b32_e32 v168, 7, v178
	v_lshlrev_b32_e32 v120, 4, v168
	v_mul_u32_u24_e32 v17, 0x1020, v168
	v_lshrrev_b32_e32 v119, 3, v178
	v_lshl_add_u32 v17, v119, 2, v17
	s_add_i32 s4, s56, 3768
	s_mov_b32 s39, 0
	s_cmpk_lt_u32 s4, 0x6c0
	s_cbranch_scc0 .Ltrq0_t1_0
	s_lshr_b32 s5, s4, 5
	s_and_b32 s6, s4, 31
	v_readlane_b32 s28, v241, 11
	v_readlane_b32 s29, v241, 12
	s_mul_i32 s9, s8, 0x3430000
	s_movk_i32 s38, 0x6860
	s_mov_b32 s2, 0
	s_mul_i32 s3, s8, 0x1b00000
	s_movk_i32 s44, 0x1000
	s_mov_b32 s39, 1
	s_branch .Ltrq0_dec_0

.Ltrq0_nosc:
	v_mov_b32_e32 v168, v16
	ds_write2_b32 v168, v100, v101 offset1:1
	ds_write2_b32 v168, v102, v103 offset0:2 offset1:3
	v_add_u32_e32 v168, 8256, v16
	ds_write2_b32 v168, v104, v105 offset1:1
	ds_write2_b32 v168, v106, v107 offset0:2 offset1:3
	v_add_u32_e32 v168, 16512, v16
	ds_write2_b32 v168, v108, v109 offset1:1
	ds_write2_b32 v168, v110, v111 offset0:2 offset1:3
	v_add_u32_e32 v168, 24768, v16
	ds_write2_b32 v168, v112, v113 offset1:1
	ds_write2_b32 v168, v114, v115 offset0:2 offset1:3
	s_add_i32 s56, s56, 52
	s_cmpk_lt_u32 s56, 0xa28
	s_cselect_b32 s7, 1, 0
	s_cbranch_scc0 .Ltrq0_nonext
	s_add_i32 s4, s56, 3768
	s_mov_b32 s39, 0
	s_cmpk_lt_u32 s4, 0x6c0
	s_cbranch_scc0 .Ltrq0_t1_1
	s_lshr_b32 s5, s4, 5
	s_and_b32 s6, s4, 31
	v_readlane_b32 s28, v241, 11
	v_readlane_b32 s29, v241, 12
	s_mul_i32 s9, s8, 0x3430000
	s_movk_i32 s38, 0x6860
	s_mov_b32 s2, 0
	s_mul_i32 s3, s8, 0x1b00000
	s_movk_i32 s44, 0x1000
	s_mov_b32 s39, 1
	s_branch .Ltrq0_dec_1

.Ltrq3a_nosc:
	v_mov_b32_e32 v168, v16
	ds_write2_b32 v168, v100, v101 offset1:1
	ds_write2_b32 v168, v102, v103 offset0:2 offset1:3
	v_add_u32_e32 v168, 8256, v16
	ds_write2_b32 v168, v104, v105 offset1:1
	ds_write2_b32 v168, v106, v107 offset0:2 offset1:3
	v_add_u32_e32 v168, 16512, v16
	ds_write2_b32 v168, v108, v109 offset1:1
	ds_write2_b32 v168, v110, v111 offset0:2 offset1:3
	v_add_u32_e32 v168, 24768, v16
	ds_write2_b32 v168, v112, v113 offset1:1
	ds_write2_b32 v168, v114, v115 offset0:2 offset1:3
	s_add_i32 s70, s70, 256
	s_cmpk_lt_u32 s70, 0x7f8
	s_cselect_b32 s7, 1, 0
	s_cbranch_scc0 .Ltrq3a_nonext
	s_add_i32 s4, s70, 1728
	s_mov_b32 s39, 0
	s_cmpk_lt_u32 s4, 0x6c0
	s_cbranch_scc0 .Ltrq3a_t1_1
	s_lshr_b32 s5, s4, 5
	s_and_b32 s6, s4, 31
	v_readlane_b32 s28, v241, 11
	v_readlane_b32 s29, v241, 12
	s_mul_i32 s9, s8, 0x3430000
	s_movk_i32 s38, 0x6860
	s_mov_b32 s2, 0
	s_mul_i32 s3, s8, 0x1b00000
	s_movk_i32 s44, 0x1000
	s_mov_b32 s39, 1
	s_branch .Ltrq3a_dec_1

.Ltrq3b_nosc:
	v_mov_b32_e32 v168, v16
	ds_write2_b32 v168, v100, v101 offset1:1
	ds_write2_b32 v168, v102, v103 offset0:2 offset1:3
	v_add_u32_e32 v168, 8256, v16
	ds_write2_b32 v168, v104, v105 offset1:1
	ds_write2_b32 v168, v106, v107 offset0:2 offset1:3
	v_add_u32_e32 v168, 16512, v16
	ds_write2_b32 v168, v108, v109 offset1:1
	ds_write2_b32 v168, v110, v111 offset0:2 offset1:3
	v_add_u32_e32 v168, 24768, v16
	ds_write2_b32 v168, v112, v113 offset1:1
	ds_write2_b32 v168, v114, v115 offset0:2 offset1:3
	s_add_i32 s68, s68, 256
	s_cmpk_lt_u32 s68, 0x7f8
	s_cselect_b32 s7, 1, 0
	s_cbranch_scc0 .Ltrq3b_nonext
	s_add_i32 s4, s68, 1728
	s_mov_b32 s39, 0
	s_cmpk_lt_u32 s4, 0x6c0
	s_cbranch_scc0 .Ltrq3b_t1_1
	s_lshr_b32 s5, s4, 5
	s_and_b32 s6, s4, 31
	v_readlane_b32 s28, v241, 11
	v_readlane_b32 s29, v241, 12
	s_mul_i32 s9, s8, 0x3430000
	s_movk_i32 s38, 0x6860
	s_mov_b32 s2, 0
	s_mul_i32 s3, s8, 0x1b00000
	s_movk_i32 s44, 0x1000
	s_mov_b32 s39, 1
	s_branch .Ltrq3b_dec_1
